# baseline (speedup 1.0000x reference)
; #define GEMM_CALL(EpiT, E, Aptr, Bptr, M_, N_, K_) do { pg8::Gemm g_{(const pg8::bf16_t*)(Aptr), (const pg8::bf16_t*)(Bptr), (M_), (N_), (K_)}; pg8::StaticOrder S_; S_.init((M_), (N_), (int)gridDim.x, (int)blockIdx.x); \
;     pg8::gemm_phase<EpiT, pg8::StaticOrder, PG8_ALIGN, PG8_SP2>((PG8_LAS unsigned char*)lds, g_, S_, (E)); } while (0)
; __global__ void __launch_bounds__(512, 2) mega_fwd(Params P) {
;     ...
;             for (int b = 0; b < 2; ++b) {
;                 const bf16_t* XBb = XB + (size_t)b * SEQ * D;
;                 { pg8::EpiBf16<0> E{Zb, DI, nullptr, 0, 0, 1.f}; GEMM_CALL(pg8::EpiBf16<0>, E, XBb, Win_t, SEQ, DI, D); }
.LBB0_425:
	s_and_b32 s4, s2, 3
.Lmy_stg1:
	s_cmp_eq_u32 s4, 0
	s_cbranch_scc1 .Lmy_stg1_done
	s_sleep 40
	s_sub_u32 s4, s4, 1
	s_branch .Lmy_stg1
